# v55 with the four unit-header vmcnt waits deleted (no register-destination load is outstanding there)
# baseline (speedup 1.0000x reference)
;     __device__ __forceinline__ size_t aoff(const Unit& u) const { return (size_t)u.pm * bm * lda * 2; }
;     __device__ __forceinline__ size_t boff(const Unit& u) const { return (size_t)u.pn * BM * ldb * 2; }
;     __device__ __forceinline__ size_t aoff(const Unit& u) const { return ((size_t)u.pm * BM * lda + (size_t)u.pn * akoff) * 2; }
;     __device__ __forceinline__ size_t boff(const Unit& u) const { return (size_t)u.pn * BM * ldb * 2; }
;     __device__ __forceinline__ size_t aoff(const Unit& u) const { return ((size_t)u.pm * BM * lda + (size_t)(u.pn >> 1) * akoff) * 2; }
;     __device__ __forceinline__ size_t boff(const Unit& u) const { return (size_t)u.pn * BM * ldb * 2; }
; #define PG8_STAGE(bufoff, gbase, voff) do { _Pragma("unroll") for (int _i = 0; _i < 2; ++_i) \
;         __builtin_amdgcn_global_load_lds((const unsigned*)((const char*)(gbase) + (voff)[_i]), (LAS unsigned*)(lds + (bufoff) + ldsw + _i * 8192), 16, 0, 0); } while (0)
; #define PG8_LDA(dst, b, h) do { _Pragma("unroll") for (int m = 0; m < NM; ++m) _Pragma("unroll") for (int k = 0; k < 2; ++k) dst[m][k] = *(const LAS bf16x8*)(lds + PG8_SA(b, h) + aoff + m * 2048 + k * 1024); } while (0)
; #define PG8_BAR __builtin_amdgcn_s_barrier()
;     ...
;         const bool has_next = S.next(ui + 1, nxt);
;         const char* nA = has_next ? (const char*)g.A + S.aoff(nxt) : cA; const char* nB = has_next ? (const char*)g.Bt + S.boff(nxt) : cB;
;         if constexpr (Epi::PRE) E.pre(lds, cur, wid);
;         for (int t = 0; t < nt; t += 2) {
;             const bool last = (t == nt - 2);
;             const char* a1 = cA + (size_t)(t + 1) * kstep;
;             const char* a2 = last ? nA : cA + (size_t)(t + 2) * kstep; const char* b2 = last ? nB : cB + (size_t)(t + 2) * kstep;
;             const char* a3 = a2 + kstep; const char* b3 = b2 + kstep;
;             if constexpr (SP2) {
;             PG8_LDB(B0, 0, 0); PG8_LDB(B1, 0, 1); PG8_SCHED; PG8_LDA(At, 0, 0); PG8_STAGE(PG8_SA(1, 1), a1 + hstepA, voffA);
;             PG8_WAIT_V(8); PG8_WAIT_L(0); PG8_BAR; PG8_MMA(0, 0, At, B0); PG8_MMA(0, 1, At, B1); PG8_BAR; PG8_SCHED;
;             PG8_LDA(At, 0, 1); PG8_STAGE(PG8_SB(0, 0), b2, voffB); PG8_STAGE(PG8_SB(0, 1), b2 + hstepB, voffB); PG8_STAGE(PG8_SA(0, 0), a2, voffA);
;             PG8_WAIT_V(8); PG8_WAIT_L(0); PG8_BAR; PG8_MMA(1, 0, At, B0); PG8_MMA(1, 1, At, B1); PG8_BAR; PG8_SCHED;
.LBB0_199:
	s_ashr_i32 s23, s22, 31
	s_lshl_b64 s[2:3], s[22:23], 20
	s_add_u32 s24, s33, s2
	s_addc_u32 s25, s36, s3
	s_and_b64 s[2:3], s[4:5], exec
	s_cselect_b32 s2, s25, s29
	s_cselect_b32 s3, s24, s28
	s_ashr_i32 s21, s20, 31
	s_lshl_b64 s[26:27], s[20:21], 20
	s_add_u32 s26, s37, s26
	s_addc_u32 s27, s38, s27
	s_and_b64 s[34:35], s[4:5], exec
	s_cselect_b32 s9, s27, s31
	s_cselect_b32 s21, s26, s30
	s_add_u32 s28, s28, 0x80080
	s_addc_u32 s29, s29, 0
	s_add_u32 s23, s30, 0x100
	s_addc_u32 s54, s31, 0
	s_mov_b32 s56, -2
	ds_read_b128 v[26:29], v172
	ds_read_b128 v[30:33], v172 offset:1024
	ds_read_b128 v[42:45], v172 offset:2048
	ds_read_b128 v[46:49], v172 offset:3072
	ds_read_b128 v[146:149], v173
	ds_read_b128 v[150:153], v173 offset:1024
	ds_read_b128 v[164:167], v173 offset:2048
	ds_read_b128 v[168:171], v173 offset:3072
	s_add_u32 s30, s28, 0xfff80080
	s_addc_u32 s31, s29, -1
	s_cmp_eq_u32 s56, 28
	s_cselect_b32 s35, s2, s31
	s_cselect_b32 s34, s3, s30
	s_cselect_b32 s31, s9, s54
	s_cselect_b32 s30, s21, s23
	s_cselect_b32 s100, -1, 0
	s_andn2_b32 s100, s100, s101
	s_add_i32 m0, s43, 0xc000
	ds_read_b128 v[178:181], v174
	ds_read_b128 v[182:185], v174 offset:1024
	ds_read_b128 v[186:189], v174 offset:2048
	ds_read_b128 v[190:193], v174 offset:3072
	ds_read_b128 v[194:197], v174 offset:4096
	ds_read_b128 v[198:201], v174 offset:5120
	ds_read_b128 v[202:205], v174 offset:6144
	ds_read_b128 v[206:209], v174 offset:7168
	global_load_lds_dwordx4 v160, s[28:29]
	s_add_i32 m0, s43, 0xe000
	s_nop 0
	global_load_lds_dwordx4 v162, s[28:29]
	s_waitcnt vmcnt(8)
	s_waitcnt lgkmcnt(0)
	s_setprio 1
	s_barrier
	v_mfma_f32_16x16x32_bf16 v[142:145], v[26:29], v[178:181], 0
	v_mfma_f32_16x16x32_bf16 v[138:141], v[42:45], v[178:181], 0
	v_mfma_f32_16x16x32_bf16 v[126:129], v[26:29], v[186:189], 0
	v_mfma_f32_16x16x32_bf16 v[122:125], v[42:45], v[186:189], 0
	v_mfma_f32_16x16x32_bf16 v[110:113], v[26:29], v[194:197], 0
	v_mfma_f32_16x16x32_bf16 v[106:109], v[42:45], v[194:197], 0
	v_mfma_f32_16x16x32_bf16 v[94:97], v[26:29], v[202:205], 0
	v_mfma_f32_16x16x32_bf16 v[90:93], v[42:45], v[202:205], 0
	v_mfma_f32_16x16x32_bf16 v[142:145], v[30:33], v[182:185], v[142:145]
	v_mfma_f32_16x16x32_bf16 v[138:141], v[46:49], v[182:185], v[138:141]
	v_mfma_f32_16x16x32_bf16 v[126:129], v[30:33], v[190:193], v[126:129]
	v_mfma_f32_16x16x32_bf16 v[122:125], v[46:49], v[190:193], v[122:125]
	v_mfma_f32_16x16x32_bf16 v[110:113], v[30:33], v[198:201], v[110:113]
	v_mfma_f32_16x16x32_bf16 v[106:109], v[46:49], v[198:201], v[106:109]
	v_mfma_f32_16x16x32_bf16 v[94:97], v[30:33], v[206:209], v[94:97]
	v_mfma_f32_16x16x32_bf16 v[90:93], v[46:49], v[206:209], v[90:93]
	s_setprio 0
	s_setprio 1
	v_mfma_f32_16x16x32_bf16 v[134:137], v[146:149], v[178:181], 0
	v_mfma_f32_16x16x32_bf16 v[130:133], v[164:167], v[178:181], 0
	v_mfma_f32_16x16x32_bf16 v[118:121], v[146:149], v[186:189], 0
	v_mfma_f32_16x16x32_bf16 v[114:117], v[164:167], v[186:189], 0
	v_mfma_f32_16x16x32_bf16 v[102:105], v[146:149], v[194:197], 0
	v_mfma_f32_16x16x32_bf16 v[98:101], v[164:167], v[194:197], 0
	v_mfma_f32_16x16x32_bf16 v[86:89], v[146:149], v[202:205], 0
	v_mfma_f32_16x16x32_bf16 v[82:85], v[164:167], v[202:205], 0
	v_mfma_f32_16x16x32_bf16 v[134:137], v[150:153], v[182:185], v[134:137]
	v_mfma_f32_16x16x32_bf16 v[130:133], v[168:171], v[182:185], v[130:133]
	v_mfma_f32_16x16x32_bf16 v[118:121], v[150:153], v[190:193], v[118:121]
	v_mfma_f32_16x16x32_bf16 v[114:117], v[168:171], v[190:193], v[114:117]
	v_mfma_f32_16x16x32_bf16 v[102:105], v[150:153], v[198:201], v[102:105]
	v_mfma_f32_16x16x32_bf16 v[98:101], v[168:171], v[198:201], v[98:101]
	v_mfma_f32_16x16x32_bf16 v[86:89], v[150:153], v[206:209], v[86:89]
	v_mfma_f32_16x16x32_bf16 v[82:85], v[168:171], v[206:209], v[82:85]
	s_barrier
	s_setprio 0
	s_mov_b32 m0, s39
	v_lshl_add_u64 v[210:211], s[30:31], 0, v[0:1]
	s_add_u32 s72, s30, 0x80000
	s_addc_u32 s73, s31, 0
	ds_read_b128 v[178:181], v174 offset:16384
	ds_read_b128 v[182:185], v174 offset:17408
	ds_read_b128 v[186:189], v174 offset:18432
	ds_read_b128 v[190:193], v174 offset:19456
	ds_read_b128 v[194:197], v174 offset:20480
	ds_read_b128 v[198:201], v174 offset:21504
	ds_read_b128 v[202:205], v174 offset:22528
	ds_read_b128 v[206:209], v174 offset:23552
	s_cmp_lg_u32 s100, 0
	s_cbranch_scc1 .Ltl_ic_0s_p
	global_load_lds_dwordx4 v0, s[30:31]
	v_lshl_add_u64 v[212:213], s[30:31], 0, v[158:159]
	s_mov_b32 m0, s40
	s_nop 0
	global_load_lds_dwordx4 v158, s[30:31]
	s_mov_b32 m0, s41
	v_lshl_add_u64 v[216:217], s[34:35], 0, v[156:157]
	global_load_lds_dwordx4 v0, s[72:73]
	s_mov_b32 m0, s42
	s_nop 0
	global_load_lds_dwordx4 v158, s[72:73]
	v_lshl_add_u64 v[214:215], s[34:35], 0, v[154:155]
	s_mov_b32 m0, s43
	s_nop 0
	global_load_lds_dwordx4 v154, s[34:35]
	s_mov_b32 m0, s44
	s_nop 0
	global_load_lds_dwordx4 v156, s[34:35]
	s_waitcnt vmcnt(8)
	s_branch .Ltl_ic_0d_p

;     __device__ __forceinline__ size_t aoff(const Unit& u) const { return (size_t)u.pm * bm * lda * 2; }
;     __device__ __forceinline__ size_t boff(const Unit& u) const { return (size_t)u.pn * BM * ldb * 2; }
;     __device__ __forceinline__ size_t aoff(const Unit& u) const { return ((size_t)u.pm * BM * lda + (size_t)u.pn * akoff) * 2; }
;     __device__ __forceinline__ size_t boff(const Unit& u) const { return (size_t)u.pn * BM * ldb * 2; }
;     __device__ __forceinline__ size_t aoff(const Unit& u) const { return ((size_t)u.pm * BM * lda + (size_t)(u.pn >> 1) * akoff) * 2; }
;     __device__ __forceinline__ size_t boff(const Unit& u) const { return (size_t)u.pn * BM * ldb * 2; }
; #define PG8_STAGE(bufoff, gbase, voff) do { _Pragma("unroll") for (int _i = 0; _i < 2; ++_i) \
;         __builtin_amdgcn_global_load_lds((const unsigned*)((const char*)(gbase) + (voff)[_i]), (LAS unsigned*)(lds + (bufoff) + ldsw + _i * 8192), 16, 0, 0); } while (0)
; #define PG8_LDA(dst, b, h) do { _Pragma("unroll") for (int m = 0; m < NM; ++m) _Pragma("unroll") for (int k = 0; k < 2; ++k) dst[m][k] = *(const LAS bf16x8*)(lds + PG8_SA(b, h) + aoff + m * 2048 + k * 1024); } while (0)
; #define PG8_LDB(dst, b, h) do { _Pragma("unroll") for (int n = 0; n < 2; ++n) _Pragma("unroll") for (int k = 0; k < 2; ++k) dst[n][k] = *(const LAS bf16x8*)(lds + PG8_SB(b, h) + boff + n * 2048 + k * 1024); } while (0)
; #define PG8_SCHED __builtin_amdgcn_sched_barrier(0)
;     ...
;         const bool has_next = S.next(ui + 1, nxt);
;         const char* nA = has_next ? (const char*)g.A + S.aoff(nxt) : cA; const char* nB = has_next ? (const char*)g.Bt + S.boff(nxt) : cB;
;         if constexpr (Epi::PRE) E.pre(lds, cur, wid);
;         for (int t = 0; t < nt; t += 2) {
;             const bool last = (t == nt - 2);
;             const char* a1 = cA + (size_t)(t + 1) * kstep;
;             const char* a2 = last ? nA : cA + (size_t)(t + 2) * kstep; const char* b2 = last ? nB : cB + (size_t)(t + 2) * kstep;
;             const char* a3 = a2 + kstep; const char* b3 = b2 + kstep;
;             if constexpr (SP2) {
;             PG8_LDB(B0, 0, 0); PG8_LDB(B1, 0, 1); PG8_SCHED; PG8_LDA(At, 0, 0); PG8_STAGE(PG8_SA(1, 1), a1 + hstepA, voffA);
.LBB0_1649:
	s_ashr_i32 s15, s14, 31
	s_lshl_b64 s[2:3], s[14:15], 20
	s_add_u32 s18, s5, s2
	s_addc_u32 s19, s26, s3
	s_and_b64 s[2:3], s[8:9], exec
	s_cselect_b32 s2, s19, s23
	s_cselect_b32 s3, s18, s22
	s_add_u32 s8, s24, 0x60080
	s_addc_u32 s9, s25, 0
	s_add_u32 s15, s22, 0x100
	s_addc_u32 s58, s23, 0
	s_mov_b32 s59, -2
	v_add_u32_e32 v102, s21, v166
	v_add_u32_e32 v126, s31, v166
	ds_read_b128 v[90:93], v102
	ds_read_b128 v[94:97], v102 offset:1024
	ds_read_b128 v[98:101], v102 offset:2048
	ds_read_b128 v[102:105], v102 offset:3072
	ds_read_b128 v[114:117], v126
	ds_read_b128 v[118:121], v126 offset:1024
	ds_read_b128 v[122:125], v126 offset:2048
	ds_read_b128 v[126:129], v126 offset:3072
	s_add_u32 s22, s8, 0xfffa0080
	s_addc_u32 s23, s9, -1
	s_cmp_eq_u32 s59, 28
	s_cselect_b32 s25, s17, s23
	s_cselect_b32 s24, s16, s22
	s_cselect_b32 s23, s2, s58
	s_cselect_b32 s22, s3, s15
	s_cselect_b32 s100, -1, 0
	s_andn2_b32 s100, s100, s101
	s_add_i32 m0, s35, 0xc000
	ds_read_b128 v[130:133], v167
	ds_read_b128 v[134:137], v167 offset:1024
	ds_read_b128 v[138:141], v167 offset:2048
	ds_read_b128 v[152:155], v167 offset:3072
	ds_read_b128 v[156:159], v167 offset:4096
	ds_read_b128 v[160:163], v167 offset:5120
	global_load_lds_dwordx4 v148, s[8:9]
	s_add_i32 m0, s35, 0xe000
	s_nop 0
	s_and_b64 vcc, exec, s[10:11]
	s_cbranch_vccz .Lnm3o_skip0_p
	global_load_lds_dwordx4 v150, s[8:9]
	s_waitcnt vmcnt(8)
	s_branch .Lnm3o_done0_p

;     __device__ __forceinline__ size_t aoff(const Unit& u) const { return (size_t)u.pm * bm * lda * 2; }
;     __device__ __forceinline__ size_t boff(const Unit& u) const { return (size_t)u.pn * BM * ldb * 2; }
;     __device__ __forceinline__ size_t aoff(const Unit& u) const { return ((size_t)u.pm * BM * lda + (size_t)u.pn * akoff) * 2; }
;     __device__ __forceinline__ size_t boff(const Unit& u) const { return (size_t)u.pn * BM * ldb * 2; }
;     __device__ __forceinline__ size_t aoff(const Unit& u) const { return ((size_t)u.pm * BM * lda + (size_t)(u.pn >> 1) * akoff) * 2; }
;     __device__ __forceinline__ size_t boff(const Unit& u) const { return (size_t)u.pn * BM * ldb * 2; }
; #define PG8_STAGE(bufoff, gbase, voff) do { _Pragma("unroll") for (int _i = 0; _i < 2; ++_i) \
;         __builtin_amdgcn_global_load_lds((const unsigned*)((const char*)(gbase) + (voff)[_i]), (LAS unsigned*)(lds + (bufoff) + ldsw + _i * 8192), 16, 0, 0); } while (0)
; #define PG8_LDA(dst, b, h) do { _Pragma("unroll") for (int m = 0; m < NM; ++m) _Pragma("unroll") for (int k = 0; k < 2; ++k) dst[m][k] = *(const LAS bf16x8*)(lds + PG8_SA(b, h) + aoff + m * 2048 + k * 1024); } while (0)
; #define PG8_BAR __builtin_amdgcn_s_barrier()
;     ...
;         const bool has_next = S.next(ui + 1, nxt);
;         const char* nA = has_next ? (const char*)g.A + S.aoff(nxt) : cA; const char* nB = has_next ? (const char*)g.Bt + S.boff(nxt) : cB;
;         if constexpr (Epi::PRE) E.pre(lds, cur, wid);
;         for (int t = 0; t < nt; t += 2) {
;             const bool last = (t == nt - 2);
;             const char* a1 = cA + (size_t)(t + 1) * kstep;
;             const char* a2 = last ? nA : cA + (size_t)(t + 2) * kstep; const char* b2 = last ? nB : cB + (size_t)(t + 2) * kstep;
;             const char* a3 = a2 + kstep; const char* b3 = b2 + kstep;
;             if constexpr (SP2) {
;             PG8_LDB(B0, 0, 0); PG8_LDB(B1, 0, 1); PG8_SCHED; PG8_LDA(At, 0, 0); PG8_STAGE(PG8_SA(1, 1), a1 + hstepA, voffA);
;             PG8_WAIT_V(8); PG8_WAIT_L(0); PG8_BAR; PG8_MMA(0, 0, At, B0); PG8_MMA(0, 1, At, B1); PG8_BAR; PG8_SCHED;
;             PG8_LDA(At, 0, 1); PG8_STAGE(PG8_SB(0, 0), b2, voffB); PG8_STAGE(PG8_SB(0, 1), b2 + hstepB, voffB); PG8_STAGE(PG8_SA(0, 0), a2, voffA);
;             PG8_WAIT_V(8); PG8_WAIT_L(0); PG8_BAR; PG8_MMA(1, 0, At, B0); PG8_MMA(1, 1, At, B1); PG8_BAR; PG8_SCHED;
.LBB0_1782:
	s_ashr_i32 s41, s40, 31
	s_lshl_b64 s[2:3], s[40:41], 20
	s_add_u32 s42, s33, s2
	s_addc_u32 s43, s48, s3
	s_and_b64 s[2:3], s[6:7], exec
	s_cselect_b32 s2, s43, s13
	s_cselect_b32 s3, s42, s12
	s_ashr_i32 s37, s36, 31
	s_lshl_b64 s[44:45], s[36:37], 20
	s_add_u32 s44, s60, s44
	s_addc_u32 s45, s63, s45
	s_and_b64 s[46:47], s[6:7], exec
	s_cselect_b32 s9, s45, s15
	s_cselect_b32 s11, s44, s14
	s_add_u32 s12, s12, 0x80080
	s_addc_u32 s13, s13, 0
	s_add_u32 s37, s14, 0x100
	s_addc_u32 s41, s15, 0
	s_mov_b32 vcc_lo, -2
	v_add_u32_e32 v0, s64, v208
	ds_read_b128 v[130:133], v0
	ds_read_b128 v[134:137], v0 offset:1024
	ds_read_b128 v[138:141], v0 offset:2048
	ds_read_b128 v[142:145], v0 offset:3072
	v_add_u32_e32 v0, s70, v208
	ds_read_b128 v[146:149], v0
	ds_read_b128 v[150:153], v0 offset:1024
	ds_read_b128 v[154:157], v0 offset:2048
	ds_read_b128 v[158:161], v0 offset:3072
	s_add_u32 s14, s12, 0xfff80080
	s_addc_u32 s15, s13, -1
	s_cmp_eq_u32 vcc_lo, 28
	s_cselect_b32 s47, s2, s15
	s_cselect_b32 s46, s3, s14
	s_cselect_b32 s15, s9, s41
	s_cselect_b32 s14, s11, s37
	s_cselect_b32 s100, -1, 0
	s_andn2_b32 s100, s100, s101
	s_add_i32 m0, s73, 0xc000
	ds_read_b128 v[162:165], v209
	ds_read_b128 v[166:169], v209 offset:1024
	ds_read_b128 v[170:173], v209 offset:2048
	ds_read_b128 v[174:177], v209 offset:3072
	ds_read_b128 v[190:193], v209 offset:4096
	ds_read_b128 v[194:197], v209 offset:5120
	ds_read_b128 v[198:201], v209 offset:6144
	ds_read_b128 v[202:205], v209 offset:7168
	global_load_lds_dwordx4 v186, s[12:13]
	s_add_i32 m0, s73, 0xe000
	s_nop 0
	global_load_lds_dwordx4 v188, s[12:13]
	s_waitcnt vmcnt(8)
	s_waitcnt lgkmcnt(0)
	s_setprio 1
	s_barrier
	v_mfma_f32_16x16x32_bf16 v[126:129], v[130:133], v[162:165], 0
	v_mfma_f32_16x16x32_bf16 v[94:97], v[138:141], v[162:165], 0
	v_mfma_f32_16x16x32_bf16 v[110:113], v[130:133], v[170:173], 0
	v_mfma_f32_16x16x32_bf16 v[70:73], v[138:141], v[170:173], 0
	v_mfma_f32_16x16x32_bf16 v[106:109], v[130:133], v[190:193], 0
	v_mfma_f32_16x16x32_bf16 v[66:69], v[138:141], v[190:193], 0
	v_mfma_f32_16x16x32_bf16 v[118:121], v[130:133], v[198:201], 0
	v_mfma_f32_16x16x32_bf16 v[86:89], v[138:141], v[198:201], 0
	v_mfma_f32_16x16x32_bf16 v[126:129], v[134:137], v[166:169], v[126:129]
	v_mfma_f32_16x16x32_bf16 v[94:97], v[142:145], v[166:169], v[94:97]
	v_mfma_f32_16x16x32_bf16 v[110:113], v[134:137], v[174:177], v[110:113]
	v_mfma_f32_16x16x32_bf16 v[70:73], v[142:145], v[174:177], v[70:73]
	v_mfma_f32_16x16x32_bf16 v[106:109], v[134:137], v[194:197], v[106:109]
	v_mfma_f32_16x16x32_bf16 v[66:69], v[142:145], v[194:197], v[66:69]
	v_mfma_f32_16x16x32_bf16 v[118:121], v[134:137], v[202:205], v[118:121]
	v_mfma_f32_16x16x32_bf16 v[86:89], v[142:145], v[202:205], v[86:89]
	s_setprio 0
	s_setprio 1
	v_mfma_f32_16x16x32_bf16 v[122:125], v[146:149], v[162:165], 0
	v_mfma_f32_16x16x32_bf16 v[90:93], v[154:157], v[162:165], 0
	v_mfma_f32_16x16x32_bf16 v[102:105], v[146:149], v[170:173], 0
	v_mfma_f32_16x16x32_bf16 v[62:65], v[154:157], v[170:173], 0
	v_mfma_f32_16x16x32_bf16 v[98:101], v[146:149], v[190:193], 0
	v_mfma_f32_16x16x32_bf16 v[58:61], v[154:157], v[190:193], 0
	v_mfma_f32_16x16x32_bf16 v[114:117], v[146:149], v[198:201], 0
	v_mfma_f32_16x16x32_bf16 v[82:85], v[154:157], v[198:201], 0
	v_mfma_f32_16x16x32_bf16 v[122:125], v[150:153], v[166:169], v[122:125]
	v_mfma_f32_16x16x32_bf16 v[90:93], v[158:161], v[166:169], v[90:93]
	v_mfma_f32_16x16x32_bf16 v[102:105], v[150:153], v[174:177], v[102:105]
	v_mfma_f32_16x16x32_bf16 v[62:65], v[158:161], v[174:177], v[62:65]
	v_mfma_f32_16x16x32_bf16 v[98:101], v[150:153], v[194:197], v[98:101]
	v_mfma_f32_16x16x32_bf16 v[58:61], v[158:161], v[194:197], v[58:61]
	v_mfma_f32_16x16x32_bf16 v[114:117], v[150:153], v[202:205], v[114:117]
	v_mfma_f32_16x16x32_bf16 v[82:85], v[158:161], v[202:205], v[82:85]
	s_barrier
	s_setprio 0
	s_mov_b32 m0, s68
	s_add_u32 s22, s14, 0x80000
	s_addc_u32 s23, s15, 0
	ds_read_b128 v[162:165], v209 offset:16384
	ds_read_b128 v[166:169], v209 offset:17408
	ds_read_b128 v[170:173], v209 offset:18432
	ds_read_b128 v[174:177], v209 offset:19456
	ds_read_b128 v[190:193], v209 offset:20480
	ds_read_b128 v[194:197], v209 offset:21504
	ds_read_b128 v[198:201], v209 offset:22528
	ds_read_b128 v[202:205], v209 offset:23552
	s_cmp_lg_u32 s100, 0
	s_cbranch_scc1 .Ltl_up_0s_p
	global_load_lds_dwordx4 v180, s[14:15]
	s_mov_b32 m0, s69
	s_nop 0
	global_load_lds_dwordx4 v184, s[14:15]
	s_mov_b32 m0, s71
	s_nop 0
	global_load_lds_dwordx4 v180, s[22:23]
	s_mov_b32 m0, s72
	s_nop 0
	global_load_lds_dwordx4 v184, s[22:23]
	s_mov_b32 m0, s73
	s_nop 0
	global_load_lds_dwordx4 v178, s[46:47]
	s_mov_b32 m0, s74
	s_nop 0
	global_load_lds_dwordx4 v182, s[46:47]
	s_waitcnt vmcnt(8)
	s_branch .Ltl_up_0d_p

;     __device__ __forceinline__ size_t aoff(const Unit& u) const { return (size_t)u.pm * bm * lda * 2; }
;     __device__ __forceinline__ size_t boff(const Unit& u) const { return (size_t)u.pn * BM * ldb * 2; }
;     __device__ __forceinline__ size_t aoff(const Unit& u) const { return ((size_t)u.pm * BM * lda + (size_t)u.pn * akoff) * 2; }
;     __device__ __forceinline__ size_t boff(const Unit& u) const { return (size_t)u.pn * BM * ldb * 2; }
;     __device__ __forceinline__ size_t aoff(const Unit& u) const { return ((size_t)u.pm * BM * lda + (size_t)(u.pn >> 1) * akoff) * 2; }
;     __device__ __forceinline__ size_t boff(const Unit& u) const { return (size_t)u.pn * BM * ldb * 2; }
; #define PG8_STAGE(bufoff, gbase, voff) do { _Pragma("unroll") for (int _i = 0; _i < 2; ++_i) \
;         __builtin_amdgcn_global_load_lds((const unsigned*)((const char*)(gbase) + (voff)[_i]), (LAS unsigned*)(lds + (bufoff) + ldsw + _i * 8192), 16, 0, 0); } while (0)
; #define PG8_LDA(dst, b, h) do { _Pragma("unroll") for (int m = 0; m < NM; ++m) _Pragma("unroll") for (int k = 0; k < 2; ++k) dst[m][k] = *(const LAS bf16x8*)(lds + PG8_SA(b, h) + aoff + m * 2048 + k * 1024); } while (0)
; #define PG8_LDB(dst, b, h) do { _Pragma("unroll") for (int n = 0; n < 2; ++n) _Pragma("unroll") for (int k = 0; k < 2; ++k) dst[n][k] = *(const LAS bf16x8*)(lds + PG8_SB(b, h) + boff + n * 2048 + k * 1024); } while (0)
; #define PG8_SCHED __builtin_amdgcn_sched_barrier(0)
;     ...
;         const bool has_next = S.next(ui + 1, nxt);
;         const char* nA = has_next ? (const char*)g.A + S.aoff(nxt) : cA; const char* nB = has_next ? (const char*)g.Bt + S.boff(nxt) : cB;
;         if constexpr (Epi::PRE) E.pre(lds, cur, wid);
;         for (int t = 0; t < nt; t += 2) {
;             const bool last = (t == nt - 2);
;             const char* a1 = cA + (size_t)(t + 1) * kstep;
;             const char* a2 = last ? nA : cA + (size_t)(t + 2) * kstep; const char* b2 = last ? nB : cB + (size_t)(t + 2) * kstep;
;             const char* a3 = a2 + kstep; const char* b3 = b2 + kstep;
;             if constexpr (SP2) {
;             PG8_LDB(B0, 0, 0); PG8_LDB(B1, 0, 1); PG8_SCHED; PG8_LDA(At, 0, 0); PG8_STAGE(PG8_SA(1, 1), a1 + hstepA, voffA);
.LBB0_2157:
	s_add_u32 s2, s16, 0x100
	s_addc_u32 s3, s17, 0
	s_mov_b32 s60, -2
	v_add_u32_e32 v102, s26, v166
	v_add_u32_e32 v126, s29, v166
	ds_read_b128 v[90:93], v102
	ds_read_b128 v[94:97], v102 offset:1024
	ds_read_b128 v[98:101], v102 offset:2048
	ds_read_b128 v[102:105], v102 offset:3072
	ds_read_b128 v[114:117], v126
	ds_read_b128 v[118:121], v126 offset:1024
	ds_read_b128 v[122:125], v126 offset:2048
	ds_read_b128 v[126:129], v126 offset:3072
	s_add_u32 s16, s14, 0x100
	s_addc_u32 s17, s15, 0
	s_cmpk_eq_i32 s60, 0x54
	s_cselect_b32 s21, s7, s17
	s_cselect_b32 s20, s6, s16
	s_cselect_b32 s19, s13, s3
	s_cselect_b32 s18, s12, s2
	s_cselect_b32 s100, -1, 0
	s_andn2_b32 s100, s100, s101
	s_add_i32 m0, s34, 0xc000
	ds_read_b128 v[130:133], v167
	ds_read_b128 v[134:137], v167 offset:1024
	ds_read_b128 v[138:141], v167 offset:2048
	ds_read_b128 v[152:155], v167 offset:3072
	ds_read_b128 v[156:159], v167 offset:4096
	ds_read_b128 v[160:163], v167 offset:5120
	global_load_lds_dwordx4 v148, s[14:15]
	s_add_i32 m0, s34, 0xe000
	s_nop 0
	s_and_b64 vcc, exec, s[8:9]
	s_cbranch_vccz .Lnm3d_skip0_p
	global_load_lds_dwordx4 v150, s[14:15]
	s_waitcnt vmcnt(8)
	s_branch .Lnm3d_done0_p
